# mixer queue: next index prefetched by thread 0 under the attention unit's epilogue (no change to item granularity)
# speedup vs baseline: 1.0071x; 1.0071x over previous
.Lam_nodma_b:
	s_sub_i32 s13, s13, 2
	s_cmp_gt_u32 s13, 0
	s_cbranch_scc1 .Lam_loop
	s_mov_b64 s[8:9], exec
	s_and_b64 exec, exec, s[4:5]
	s_cbranch_execz .Lam_pfx
	v_mov_b32_e32 v249, 1
	global_atomic_add v249, v97, v249, s[66:67] sc0
.Lam_pfx:
	s_mov_b64 exec, s[8:9]
	v_writelane_b32 v251, 1, 20
	v_and_b32_e32 v240, 31, v96
	v_lshl_add_u32 v241, v240, 2, s50
	ds_write_b32 v241, v239 offset:128
	v_lshrrev_b32_e32 v241, 5, v96
	v_lshl_add_u32 v242, v241, 4, s50
	s_waitcnt lgkmcnt(0)
	ds_read_b128 v[212:215], v242 offset:128
	ds_read_b128 v[216:219], v242 offset:160
	ds_read_b128 v[220:223], v242 offset:192
	ds_read_b128 v[224:227], v242 offset:224
	s_lshl_b32 s37, s36, 5
	v_lshl_add_u32 v241, v241, 2, s37
	v_lshlrev_b32_e32 v241, 13, v241
	v_lshl_add_u32 v241, v240, 1, v241
	s_waitcnt lgkmcnt(0)
	v_rcp_f32_e32 v212, v212
	v_rcp_f32_e32 v213, v213
	v_rcp_f32_e32 v214, v214
	v_rcp_f32_e32 v215, v215
	v_rcp_f32_e32 v216, v216
	v_rcp_f32_e32 v217, v217
	v_rcp_f32_e32 v218, v218
	v_rcp_f32_e32 v219, v219
	v_rcp_f32_e32 v220, v220
	v_rcp_f32_e32 v221, v221
	v_rcp_f32_e32 v222, v222
	v_rcp_f32_e32 v223, v223
	v_rcp_f32_e32 v224, v224
	v_rcp_f32_e32 v225, v225
	v_rcp_f32_e32 v226, v226
	v_rcp_f32_e32 v227, v227
	s_nop 0
	v_mov_b32_e32 v240, v241
	v_mul_f32_e32 v162, v0, v212
	v_cvt_pk_bf16_f32 v162, v162, v162
	global_store_short v240, v162, s[22:23]
	v_mul_f32_e32 v163, v16, v212
	v_cvt_pk_bf16_f32 v163, v163, v163
	global_store_short v240, v163, s[22:23] offset:64
	v_mul_f32_e32 v164, v32, v212
	v_cvt_pk_bf16_f32 v164, v164, v164
	global_store_short v240, v164, s[22:23] offset:128
	v_mul_f32_e32 v165, v48, v212
	v_cvt_pk_bf16_f32 v165, v165, v165
	global_store_short v240, v165, s[22:23] offset:192
	v_mul_f32_e32 v166, v64, v212
	v_cvt_pk_bf16_f32 v166, v166, v166
	global_store_short v240, v166, s[22:23] offset:256
	v_mul_f32_e32 v167, v80, v212
	v_cvt_pk_bf16_f32 v167, v167, v167
	global_store_short v240, v167, s[22:23] offset:320
	v_mul_f32_e32 v168, v98, v212
	v_cvt_pk_bf16_f32 v168, v168, v168
	global_store_short v240, v168, s[22:23] offset:384
	v_mul_f32_e32 v169, v114, v212
	v_cvt_pk_bf16_f32 v169, v169, v169
	global_store_short v240, v169, s[22:23] offset:448
	v_add_u32_e32 v240, 0x2000, v241
	v_mul_f32_e32 v170, v1, v213
	v_cvt_pk_bf16_f32 v170, v170, v170
	global_store_short v240, v170, s[22:23]
	v_mul_f32_e32 v171, v17, v213
	v_cvt_pk_bf16_f32 v171, v171, v171
	global_store_short v240, v171, s[22:23] offset:64
	v_mul_f32_e32 v172, v33, v213
	v_cvt_pk_bf16_f32 v172, v172, v172
	global_store_short v240, v172, s[22:23] offset:128
	v_mul_f32_e32 v173, v49, v213
	v_cvt_pk_bf16_f32 v173, v173, v173
	global_store_short v240, v173, s[22:23] offset:192
	v_mul_f32_e32 v174, v65, v213
	v_cvt_pk_bf16_f32 v174, v174, v174
	global_store_short v240, v174, s[22:23] offset:256
	v_mul_f32_e32 v175, v81, v213
	v_cvt_pk_bf16_f32 v175, v175, v175
	global_store_short v240, v175, s[22:23] offset:320
	v_mul_f32_e32 v176, v99, v213
	v_cvt_pk_bf16_f32 v176, v176, v176
	global_store_short v240, v176, s[22:23] offset:384
	v_mul_f32_e32 v177, v115, v213
	v_cvt_pk_bf16_f32 v177, v177, v177
	global_store_short v240, v177, s[22:23] offset:448
	v_add_u32_e32 v240, 0x4000, v241
	v_mul_f32_e32 v178, v2, v214
	v_cvt_pk_bf16_f32 v178, v178, v178
	global_store_short v240, v178, s[22:23]
	v_mul_f32_e32 v179, v18, v214
	v_cvt_pk_bf16_f32 v179, v179, v179
	global_store_short v240, v179, s[22:23] offset:64
	v_mul_f32_e32 v180, v34, v214
	v_cvt_pk_bf16_f32 v180, v180, v180
	global_store_short v240, v180, s[22:23] offset:128
	v_mul_f32_e32 v181, v50, v214
	v_cvt_pk_bf16_f32 v181, v181, v181
	global_store_short v240, v181, s[22:23] offset:192
	v_mul_f32_e32 v182, v66, v214
	v_cvt_pk_bf16_f32 v182, v182, v182
	global_store_short v240, v182, s[22:23] offset:256
	v_mul_f32_e32 v183, v82, v214
	v_cvt_pk_bf16_f32 v183, v183, v183
	global_store_short v240, v183, s[22:23] offset:320
	v_mul_f32_e32 v184, v100, v214
	v_cvt_pk_bf16_f32 v184, v184, v184
	global_store_short v240, v184, s[22:23] offset:384
	v_mul_f32_e32 v185, v116, v214
	v_cvt_pk_bf16_f32 v185, v185, v185
	global_store_short v240, v185, s[22:23] offset:448
	v_add_u32_e32 v240, 0x6000, v241
	v_mul_f32_e32 v186, v3, v215
	v_cvt_pk_bf16_f32 v186, v186, v186
	global_store_short v240, v186, s[22:23]
	v_mul_f32_e32 v187, v19, v215
	v_cvt_pk_bf16_f32 v187, v187, v187
	global_store_short v240, v187, s[22:23] offset:64
	v_mul_f32_e32 v188, v35, v215
	v_cvt_pk_bf16_f32 v188, v188, v188
	global_store_short v240, v188, s[22:23] offset:128
	v_mul_f32_e32 v189, v51, v215
	v_cvt_pk_bf16_f32 v189, v189, v189
	global_store_short v240, v189, s[22:23] offset:192
	v_mul_f32_e32 v190, v67, v215
	v_cvt_pk_bf16_f32 v190, v190, v190
	global_store_short v240, v190, s[22:23] offset:256
	v_mul_f32_e32 v191, v83, v215
	v_cvt_pk_bf16_f32 v191, v191, v191
	global_store_short v240, v191, s[22:23] offset:320
	v_mul_f32_e32 v192, v101, v215
	v_cvt_pk_bf16_f32 v192, v192, v192
	global_store_short v240, v192, s[22:23] offset:384
	v_mul_f32_e32 v193, v117, v215
	v_cvt_pk_bf16_f32 v193, v193, v193
	global_store_short v240, v193, s[22:23] offset:448
	v_add_u32_e32 v240, 0x10000, v241
	v_mul_f32_e32 v162, v4, v216
	v_cvt_pk_bf16_f32 v162, v162, v162
	global_store_short v240, v162, s[22:23]
	v_mul_f32_e32 v163, v20, v216
	v_cvt_pk_bf16_f32 v163, v163, v163
	global_store_short v240, v163, s[22:23] offset:64
	v_mul_f32_e32 v164, v36, v216
	v_cvt_pk_bf16_f32 v164, v164, v164
	global_store_short v240, v164, s[22:23] offset:128
	v_mul_f32_e32 v165, v52, v216
	v_cvt_pk_bf16_f32 v165, v165, v165
	global_store_short v240, v165, s[22:23] offset:192
	v_mul_f32_e32 v166, v68, v216
	v_cvt_pk_bf16_f32 v166, v166, v166
	global_store_short v240, v166, s[22:23] offset:256
	v_mul_f32_e32 v167, v84, v216
	v_cvt_pk_bf16_f32 v167, v167, v167
	global_store_short v240, v167, s[22:23] offset:320
	v_mul_f32_e32 v168, v102, v216
	v_cvt_pk_bf16_f32 v168, v168, v168
	global_store_short v240, v168, s[22:23] offset:384
	v_mul_f32_e32 v169, v118, v216
	v_cvt_pk_bf16_f32 v169, v169, v169
	global_store_short v240, v169, s[22:23] offset:448
	v_add_u32_e32 v240, 0x12000, v241
	v_mul_f32_e32 v170, v5, v217
	v_cvt_pk_bf16_f32 v170, v170, v170
	global_store_short v240, v170, s[22:23]
	v_mul_f32_e32 v171, v21, v217
	v_cvt_pk_bf16_f32 v171, v171, v171
	global_store_short v240, v171, s[22:23] offset:64
	v_mul_f32_e32 v172, v37, v217
	v_cvt_pk_bf16_f32 v172, v172, v172
	global_store_short v240, v172, s[22:23] offset:128
	v_mul_f32_e32 v173, v53, v217
	v_cvt_pk_bf16_f32 v173, v173, v173
	global_store_short v240, v173, s[22:23] offset:192
	v_mul_f32_e32 v174, v69, v217
	v_cvt_pk_bf16_f32 v174, v174, v174
	global_store_short v240, v174, s[22:23] offset:256
	v_mul_f32_e32 v175, v85, v217
	v_cvt_pk_bf16_f32 v175, v175, v175
	global_store_short v240, v175, s[22:23] offset:320
	v_mul_f32_e32 v176, v103, v217
	v_cvt_pk_bf16_f32 v176, v176, v176
	global_store_short v240, v176, s[22:23] offset:384
	v_mul_f32_e32 v177, v119, v217
	v_cvt_pk_bf16_f32 v177, v177, v177
	global_store_short v240, v177, s[22:23] offset:448
	v_add_u32_e32 v240, 0x14000, v241
	v_mul_f32_e32 v178, v6, v218
	v_cvt_pk_bf16_f32 v178, v178, v178
	global_store_short v240, v178, s[22:23]
	v_mul_f32_e32 v179, v22, v218
	v_cvt_pk_bf16_f32 v179, v179, v179
	global_store_short v240, v179, s[22:23] offset:64
	v_mul_f32_e32 v180, v38, v218
	v_cvt_pk_bf16_f32 v180, v180, v180
	global_store_short v240, v180, s[22:23] offset:128
	v_mul_f32_e32 v181, v54, v218
	v_cvt_pk_bf16_f32 v181, v181, v181
	global_store_short v240, v181, s[22:23] offset:192
	v_mul_f32_e32 v182, v70, v218
	v_cvt_pk_bf16_f32 v182, v182, v182
	global_store_short v240, v182, s[22:23] offset:256
	v_mul_f32_e32 v183, v86, v218
	v_cvt_pk_bf16_f32 v183, v183, v183
	global_store_short v240, v183, s[22:23] offset:320
	v_mul_f32_e32 v184, v104, v218
	v_cvt_pk_bf16_f32 v184, v184, v184
	global_store_short v240, v184, s[22:23] offset:384
	v_mul_f32_e32 v185, v120, v218
	v_cvt_pk_bf16_f32 v185, v185, v185
	global_store_short v240, v185, s[22:23] offset:448
	v_add_u32_e32 v240, 0x16000, v241
	v_mul_f32_e32 v186, v7, v219
	v_cvt_pk_bf16_f32 v186, v186, v186
	global_store_short v240, v186, s[22:23]
	v_mul_f32_e32 v187, v23, v219
	v_cvt_pk_bf16_f32 v187, v187, v187
	global_store_short v240, v187, s[22:23] offset:64
	v_mul_f32_e32 v188, v39, v219
	v_cvt_pk_bf16_f32 v188, v188, v188
	global_store_short v240, v188, s[22:23] offset:128
	v_mul_f32_e32 v189, v55, v219
	v_cvt_pk_bf16_f32 v189, v189, v189
	global_store_short v240, v189, s[22:23] offset:192
	v_mul_f32_e32 v190, v71, v219
	v_cvt_pk_bf16_f32 v190, v190, v190
	global_store_short v240, v190, s[22:23] offset:256
	v_mul_f32_e32 v191, v87, v219
	v_cvt_pk_bf16_f32 v191, v191, v191
	global_store_short v240, v191, s[22:23] offset:320
	v_mul_f32_e32 v192, v105, v219
	v_cvt_pk_bf16_f32 v192, v192, v192
	global_store_short v240, v192, s[22:23] offset:384
	v_mul_f32_e32 v193, v121, v219
	v_cvt_pk_bf16_f32 v193, v193, v193
	global_store_short v240, v193, s[22:23] offset:448
	v_add_u32_e32 v240, 0x20000, v241
	v_mul_f32_e32 v162, v8, v220
	v_cvt_pk_bf16_f32 v162, v162, v162
	global_store_short v240, v162, s[22:23]
	v_mul_f32_e32 v163, v24, v220
	v_cvt_pk_bf16_f32 v163, v163, v163
	global_store_short v240, v163, s[22:23] offset:64
	v_mul_f32_e32 v164, v40, v220
	v_cvt_pk_bf16_f32 v164, v164, v164
	global_store_short v240, v164, s[22:23] offset:128
	v_mul_f32_e32 v165, v56, v220
	v_cvt_pk_bf16_f32 v165, v165, v165
	global_store_short v240, v165, s[22:23] offset:192
	v_mul_f32_e32 v166, v72, v220
	v_cvt_pk_bf16_f32 v166, v166, v166
	global_store_short v240, v166, s[22:23] offset:256
	v_mul_f32_e32 v167, v88, v220
	v_cvt_pk_bf16_f32 v167, v167, v167
	global_store_short v240, v167, s[22:23] offset:320
	v_mul_f32_e32 v168, v106, v220
	v_cvt_pk_bf16_f32 v168, v168, v168
	global_store_short v240, v168, s[22:23] offset:384
	v_mul_f32_e32 v169, v122, v220
	v_cvt_pk_bf16_f32 v169, v169, v169
	global_store_short v240, v169, s[22:23] offset:448
	v_add_u32_e32 v240, 0x22000, v241
	v_mul_f32_e32 v170, v9, v221
	v_cvt_pk_bf16_f32 v170, v170, v170
	global_store_short v240, v170, s[22:23]
	v_mul_f32_e32 v171, v25, v221
	v_cvt_pk_bf16_f32 v171, v171, v171
	global_store_short v240, v171, s[22:23] offset:64
	v_mul_f32_e32 v172, v41, v221
	v_cvt_pk_bf16_f32 v172, v172, v172
	global_store_short v240, v172, s[22:23] offset:128
	v_mul_f32_e32 v173, v57, v221
	v_cvt_pk_bf16_f32 v173, v173, v173
	global_store_short v240, v173, s[22:23] offset:192
	v_mul_f32_e32 v174, v73, v221
	v_cvt_pk_bf16_f32 v174, v174, v174
	global_store_short v240, v174, s[22:23] offset:256
	v_mul_f32_e32 v175, v89, v221
	v_cvt_pk_bf16_f32 v175, v175, v175
	global_store_short v240, v175, s[22:23] offset:320
	v_mul_f32_e32 v176, v107, v221
	v_cvt_pk_bf16_f32 v176, v176, v176
	global_store_short v240, v176, s[22:23] offset:384
	v_mul_f32_e32 v177, v123, v221
	v_cvt_pk_bf16_f32 v177, v177, v177
	global_store_short v240, v177, s[22:23] offset:448
	v_add_u32_e32 v240, 0x24000, v241
	v_mul_f32_e32 v178, v10, v222
	v_cvt_pk_bf16_f32 v178, v178, v178
	global_store_short v240, v178, s[22:23]
	v_mul_f32_e32 v179, v26, v222
	v_cvt_pk_bf16_f32 v179, v179, v179
	global_store_short v240, v179, s[22:23] offset:64
	v_mul_f32_e32 v180, v42, v222
	v_cvt_pk_bf16_f32 v180, v180, v180
	global_store_short v240, v180, s[22:23] offset:128
	v_mul_f32_e32 v181, v58, v222
	v_cvt_pk_bf16_f32 v181, v181, v181
	global_store_short v240, v181, s[22:23] offset:192
	v_mul_f32_e32 v182, v74, v222
	v_cvt_pk_bf16_f32 v182, v182, v182
	global_store_short v240, v182, s[22:23] offset:256
	v_mul_f32_e32 v183, v90, v222
	v_cvt_pk_bf16_f32 v183, v183, v183
	global_store_short v240, v183, s[22:23] offset:320
	v_mul_f32_e32 v184, v108, v222
	v_cvt_pk_bf16_f32 v184, v184, v184
	global_store_short v240, v184, s[22:23] offset:384
	v_mul_f32_e32 v185, v124, v222
	v_cvt_pk_bf16_f32 v185, v185, v185
	global_store_short v240, v185, s[22:23] offset:448
	v_add_u32_e32 v240, 0x26000, v241
	v_mul_f32_e32 v186, v11, v223
	v_cvt_pk_bf16_f32 v186, v186, v186
	global_store_short v240, v186, s[22:23]
	v_mul_f32_e32 v187, v27, v223
	v_cvt_pk_bf16_f32 v187, v187, v187
	global_store_short v240, v187, s[22:23] offset:64
	v_mul_f32_e32 v188, v43, v223
	v_cvt_pk_bf16_f32 v188, v188, v188
	global_store_short v240, v188, s[22:23] offset:128
	v_mul_f32_e32 v189, v59, v223
	v_cvt_pk_bf16_f32 v189, v189, v189
	global_store_short v240, v189, s[22:23] offset:192
	v_mul_f32_e32 v190, v75, v223
	v_cvt_pk_bf16_f32 v190, v190, v190
	global_store_short v240, v190, s[22:23] offset:256
	v_mul_f32_e32 v191, v91, v223
	v_cvt_pk_bf16_f32 v191, v191, v191
	global_store_short v240, v191, s[22:23] offset:320
	v_mul_f32_e32 v192, v109, v223
	v_cvt_pk_bf16_f32 v192, v192, v192
	global_store_short v240, v192, s[22:23] offset:384
	v_mul_f32_e32 v193, v125, v223
	v_cvt_pk_bf16_f32 v193, v193, v193
	global_store_short v240, v193, s[22:23] offset:448
	v_add_u32_e32 v240, 0x30000, v241
	v_mul_f32_e32 v162, v12, v224
	v_cvt_pk_bf16_f32 v162, v162, v162
	global_store_short v240, v162, s[22:23]
	v_mul_f32_e32 v163, v28, v224
	v_cvt_pk_bf16_f32 v163, v163, v163
	global_store_short v240, v163, s[22:23] offset:64
	v_mul_f32_e32 v164, v44, v224
	v_cvt_pk_bf16_f32 v164, v164, v164
	global_store_short v240, v164, s[22:23] offset:128
	v_mul_f32_e32 v165, v60, v224
	v_cvt_pk_bf16_f32 v165, v165, v165
	global_store_short v240, v165, s[22:23] offset:192
	v_mul_f32_e32 v166, v76, v224
	v_cvt_pk_bf16_f32 v166, v166, v166
	global_store_short v240, v166, s[22:23] offset:256
	v_mul_f32_e32 v167, v92, v224
	v_cvt_pk_bf16_f32 v167, v167, v167
	global_store_short v240, v167, s[22:23] offset:320
	v_mul_f32_e32 v168, v110, v224
	v_cvt_pk_bf16_f32 v168, v168, v168
	global_store_short v240, v168, s[22:23] offset:384
	v_mul_f32_e32 v169, v126, v224
	v_cvt_pk_bf16_f32 v169, v169, v169
	global_store_short v240, v169, s[22:23] offset:448
	v_add_u32_e32 v240, 0x32000, v241
	v_mul_f32_e32 v170, v13, v225
	v_cvt_pk_bf16_f32 v170, v170, v170
	global_store_short v240, v170, s[22:23]
	v_mul_f32_e32 v171, v29, v225
	v_cvt_pk_bf16_f32 v171, v171, v171
	global_store_short v240, v171, s[22:23] offset:64
	v_mul_f32_e32 v172, v45, v225
	v_cvt_pk_bf16_f32 v172, v172, v172
	global_store_short v240, v172, s[22:23] offset:128
	v_mul_f32_e32 v173, v61, v225
	v_cvt_pk_bf16_f32 v173, v173, v173
	global_store_short v240, v173, s[22:23] offset:192
	v_mul_f32_e32 v174, v77, v225
	v_cvt_pk_bf16_f32 v174, v174, v174
	global_store_short v240, v174, s[22:23] offset:256
	v_mul_f32_e32 v175, v93, v225
	v_cvt_pk_bf16_f32 v175, v175, v175
	global_store_short v240, v175, s[22:23] offset:320
	v_mul_f32_e32 v176, v111, v225
	v_cvt_pk_bf16_f32 v176, v176, v176
	global_store_short v240, v176, s[22:23] offset:384
	v_mul_f32_e32 v177, v127, v225
	v_cvt_pk_bf16_f32 v177, v177, v177
	global_store_short v240, v177, s[22:23] offset:448
	v_add_u32_e32 v240, 0x34000, v241
	v_mul_f32_e32 v178, v14, v226
	v_cvt_pk_bf16_f32 v178, v178, v178
	global_store_short v240, v178, s[22:23]
	v_mul_f32_e32 v179, v30, v226
	v_cvt_pk_bf16_f32 v179, v179, v179
	global_store_short v240, v179, s[22:23] offset:64
	v_mul_f32_e32 v180, v46, v226
	v_cvt_pk_bf16_f32 v180, v180, v180
	global_store_short v240, v180, s[22:23] offset:128
	v_mul_f32_e32 v181, v62, v226
	v_cvt_pk_bf16_f32 v181, v181, v181
	global_store_short v240, v181, s[22:23] offset:192
	v_mul_f32_e32 v182, v78, v226
	v_cvt_pk_bf16_f32 v182, v182, v182
	global_store_short v240, v182, s[22:23] offset:256
	v_mul_f32_e32 v183, v94, v226
	v_cvt_pk_bf16_f32 v183, v183, v183
	global_store_short v240, v183, s[22:23] offset:320
	v_mul_f32_e32 v184, v112, v226
	v_cvt_pk_bf16_f32 v184, v184, v184
	global_store_short v240, v184, s[22:23] offset:384
	v_mul_f32_e32 v185, v128, v226
	v_cvt_pk_bf16_f32 v185, v185, v185
	global_store_short v240, v185, s[22:23] offset:448
	v_add_u32_e32 v240, 0x36000, v241
	v_mul_f32_e32 v186, v15, v227
	v_cvt_pk_bf16_f32 v186, v186, v186
	global_store_short v240, v186, s[22:23]
	v_mul_f32_e32 v187, v31, v227
	v_cvt_pk_bf16_f32 v187, v187, v187
	global_store_short v240, v187, s[22:23] offset:64
	v_mul_f32_e32 v188, v47, v227
	v_cvt_pk_bf16_f32 v188, v188, v188
	global_store_short v240, v188, s[22:23] offset:128
	v_mul_f32_e32 v189, v63, v227
	v_cvt_pk_bf16_f32 v189, v189, v189
	global_store_short v240, v189, s[22:23] offset:192
	v_mul_f32_e32 v190, v79, v227
	v_cvt_pk_bf16_f32 v190, v190, v190
	global_store_short v240, v190, s[22:23] offset:256
	v_mul_f32_e32 v191, v95, v227
	v_cvt_pk_bf16_f32 v191, v191, v191
	global_store_short v240, v191, s[22:23] offset:320
	v_mul_f32_e32 v192, v113, v227
	v_cvt_pk_bf16_f32 v192, v192, v192
	global_store_short v240, v192, s[22:23] offset:384
	v_mul_f32_e32 v193, v129, v227
	v_cvt_pk_bf16_f32 v193, v193, v193
	global_store_short v240, v193, s[22:23] offset:448
	s_waitcnt lgkmcnt(0)
	s_barrier
	s_brev_b32 s30, 64
	v_readlane_b32 s31, v254, 63
	s_movk_i32 s61, 0x1000
	s_mov_b64 s[6:7], 0
